# v41
# speedup vs baseline: 1.0009x; 1.0009x over previous
; #define MFMA32(a, b, c) __builtin_amdgcn_mfma_f32_32x32x16_bf16((a), (b), (c), 0, 0, 0)
;   const int r = lane & 31, hh = lane >> 5;
;   const bf16x8* fq = (const bf16x8*)(smem + DS_FRAGQ);
;   bf16x8 a[4], an[4];
;   int kt = w;
;   if (kt < nt) for (int s = 0; s < 4; ++s) a[s] = ldg<bf16x8>(Ikb + (size_t)(kt * 32 + r) * 64 + 16 * s + 8 * hh);
;   for (; kt < nt; kt += stride) {
;     const bool more = kt + stride < nt;
;     if (more) for (int s = 0; s < 4; ++s) an[s] = ldg<bf16x8>(Ikb + (size_t)((kt + stride) * 32 + r) * 64 + 16 * s + 8 * hh);
;     f32x16 sc;
;     for (int i = 0; i < 16; ++i) sc[i] = 0.f;
;     {
;       const bf16x8* fb = (const bf16x8*)(smem + DS_QBAR);
;       #pragma unroll
;       for (int s = 0; s < 4; ++s) sc = MFMA32(a[s], fb[s * 64 + lane], sc);
;       for (int i = 0; i < 16; ++i) sc[i] *= 0.5f;
;     }
;     #pragma unroll
;     for (int hd = 0; hd < 8; ++hd) {
;       f32x16 acc;
;       for (int i = 0; i < 16; ++i) acc[i] = 0.f;
;       #pragma unroll
;       for (int s = 0; s < 4; ++s) acc = MFMA32(a[s], fq[(hd * 4 + s) * 64 + lane], acc);
.Lhf_entry:
	s_nop 0
	v_readfirstlane_b32 s100, v207
	s_nop 3
	ds_read_b128 v[100:103], v200
	ds_read_b128 v[104:107], v200 offset:1024
	ds_read_b128 v[108:111], v200 offset:2048
	ds_read_b128 v[112:115], v200 offset:3072
	ds_read_b128 v[116:119], v199 offset:32768
	ds_read_b128 v[120:123], v199 offset:33792
	ds_read_b128 v[124:127], v199 offset:34816
	ds_read_b128 v[208:211], v199 offset:35840
	ds_read_b128 v[212:215], v199 offset:36864
	ds_read_b128 v[216:219], v199 offset:37888
	ds_read_b128 v[220:223], v199 offset:38912
	ds_read_b128 v[224:227], v199 offset:39936
	ds_read_b128 v[228:231], v199 offset:40960
	ds_read_b128 v[232:235], v199 offset:41984
	ds_read_b128 v[236:239], v199 offset:43008
	ds_read_b128 v[240:243], v199 offset:44032
	s_waitcnt lgkmcnt(0)
	v_readfirstlane_b32 s101, v178
	s_nop 3
	s_cmpk_lt_u32 s101, 0x100
	s_cbranch_scc1 .Lhf_top
	s_sleep 10
